# weight conversion items: the 16 per-row norm gains requested at once instead of two at a time with a wait after each pair
# speedup vs baseline: 1.0301x; 1.0079x over previous
; #define LAS __attribute__((address_space(3)))
; __device__ __forceinline__ int pair_row(int n0, int H) { const int gsel = n0 >= H ? 1 : 0, nn = n0 - gsel * H; return (nn >> 7) * 256 + gsel * 128 + (nn & 127); }
; __device__ __forceinline__ void tr_item(const float* __restrict__ W, int K, int N, bf16_t* __restrict__ WT, int k0, int n0, int drow0, const float* gain, LAS float* scr, int lane) {
;     f32x4 v[16];
;     const int kq_ = lane >> 4, nn = (lane & 15) * 4;
; #pragma unroll
;     for (int i = 0; i < 16; ++i) v[i] = __builtin_nontemporal_load((const f32x4*)(W + (size_t)(k0 + 4 * i + kq_) * N + n0 + nn));
; #pragma unroll
;     for (int i = 0; i < 16; ++i) { const int kk = 4 * i + kq_; f32x4 t = v[i];
;         if (gain) t = t * gain[k0 + kk];
;         LAS float* s = scr + kk * 65 + nn; s[0] = t[0]; s[1] = t[1]; s[2] = t[2]; s[3] = t[3]; }
; __device__ __forceinline__ bool tr_matrix(int& it, const float* W, int K, int N, bf16_t* WT, int drow_base, int pairH, const float* gain, LAS float* scr, int lane) {
;     const int nb = N / 64, cnt = (K / 64) * nb;
;     if (it >= cnt) { it -= cnt; return false; }
;     const int kb = it / nb, n0 = (it % nb) * 64;
;     tr_item(W, K, N, WT, kb * 64, n0, drow_base + (pairH ? pair_row(n0, pairH) : n0), gain, scr, lane);
;     return true;
.LBB0_33:
	s_and_b64 vcc, exec, s[4:5]
	s_cbranch_vccz .LBB0_25
	s_mov_b32 s12, 0
	s_mov_b32 s4, 0
	s_mov_b32 s10, 0
	s_cmpk_gt_i32 s29, 0x15ff
	s_cbranch_scc1 .LBB0_25
	s_ashr_i32 s13, s12, 31
	s_lshl_b64 s[12:13], s[12:13], 3
	s_add_u32 s12, s0, s12
	s_addc_u32 s13, s1, s13
	s_ashr_i32 s5, s4, 31
	s_lshl_b64 s[4:5], s[4:5], 3
	s_add_u32 s4, s0, s4
	s_addc_u32 s5, s1, s5
	s_ashr_i32 s11, s10, 31
	s_lshl_b64 s[10:11], s[10:11], 3
	s_add_u32 s10, s0, s10
	s_addc_u32 s11, s1, s11
	s_load_dwordx2 s[16:17], s[12:13], 0xa0
	s_load_dwordx2 s[14:15], s[10:11], 0x10
	s_mul_hi_i32 s10, s29, 0x2e8ba2e9
	s_lshr_b32 s11, s10, 31
	s_ashr_i32 s10, s10, 5
	s_add_i32 s10, s10, s11
	s_mul_i32 s11, s10, 0xb0
	s_sub_i32 s27, s29, s11
	s_lshl_b32 s12, s27, 6
	s_ashr_i32 s13, s12, 31
	s_lshl_b32 s10, s10, 6
	s_lshl_b64 s[18:19], s[12:13], 2
	s_waitcnt lgkmcnt(0)
	s_add_u32 s16, s16, s18
	s_addc_u32 s17, s17, s19
	v_mov_b32_e32 v75, v71
	v_or_b32_e32 v64, s10, v68
	v_lshl_add_u64 v[0:1], s[16:17], 0, v[74:75]
	v_mad_i64_i32 v[2:3], s[16:17], v64, s26, v[0:1]
	v_or_b32_e32 v4, 4, v64
	v_mad_i64_i32 v[4:5], s[16:17], v4, s26, v[0:1]
	global_load_dwordx4 v[56:59], v[2:3], off nt
	global_load_dwordx4 v[60:63], v[4:5], off nt
	v_or_b32_e32 v2, 8, v64
	v_mad_i64_i32 v[2:3], s[16:17], v2, s26, v[0:1]
	v_or_b32_e32 v4, 12, v64
	v_mad_i64_i32 v[4:5], s[16:17], v4, s26, v[0:1]
	global_load_dwordx4 v[48:51], v[2:3], off nt
	global_load_dwordx4 v[52:55], v[4:5], off nt
	v_or_b32_e32 v2, 16, v64
	v_mad_i64_i32 v[2:3], s[16:17], v2, s26, v[0:1]
	v_or_b32_e32 v4, 20, v64
	v_mad_i64_i32 v[4:5], s[16:17], v4, s26, v[0:1]
	global_load_dwordx4 v[40:43], v[2:3], off nt
	global_load_dwordx4 v[44:47], v[4:5], off nt
	v_or_b32_e32 v2, 24, v64
	v_mad_i64_i32 v[2:3], s[16:17], v2, s26, v[0:1]
	v_or_b32_e32 v4, 28, v64
	v_mad_i64_i32 v[4:5], s[16:17], v4, s26, v[0:1]
	global_load_dwordx4 v[32:35], v[2:3], off nt
	global_load_dwordx4 v[36:39], v[4:5], off nt
	v_or_b32_e32 v2, 32, v64
	v_mad_i64_i32 v[2:3], s[16:17], v2, s26, v[0:1]
	v_or_b32_e32 v4, 36, v64
	v_mad_i64_i32 v[4:5], s[16:17], v4, s26, v[0:1]
	global_load_dwordx4 v[24:27], v[2:3], off nt
	global_load_dwordx4 v[28:31], v[4:5], off nt
	v_or_b32_e32 v2, 40, v64
	v_mad_i64_i32 v[2:3], s[16:17], v2, s26, v[0:1]
	v_or_b32_e32 v4, 44, v64
	v_mad_i64_i32 v[4:5], s[16:17], v4, s26, v[0:1]
	global_load_dwordx4 v[16:19], v[2:3], off nt
	global_load_dwordx4 v[20:23], v[4:5], off nt
	v_or_b32_e32 v2, 48, v64
	v_mad_i64_i32 v[2:3], s[16:17], v2, s26, v[0:1]
	v_or_b32_e32 v4, 52, v64
	v_mad_i64_i32 v[4:5], s[16:17], v4, s26, v[0:1]
	global_load_dwordx4 v[8:11], v[2:3], off nt
	global_load_dwordx4 v[12:15], v[4:5], off nt
	v_or_b32_e32 v2, 56, v64
	v_mad_i64_i32 v[66:67], s[16:17], v2, s26, v[0:1]
	v_or_b32_e32 v2, 60, v64
	v_mad_i64_i32 v[76:77], s[16:17], v2, s26, v[0:1]
	global_load_dwordx4 v[0:3], v[66:67], off nt
	global_load_dwordx4 v[4:7], v[76:77], off nt
	s_cmp_lg_u64 s[14:15], 0
	s_cselect_b64 s[18:19], -1, 0
	s_cmp_eq_u64 s[14:15], 0
	s_cbranch_scc1 .LBB0_58
	s_ashr_i32 s11, s10, 31
	v_ashrrev_i32_e32 v65, 31, v64
	v_lshl_add_u64 v[66:67], s[10:11], 0, v[68:69]
	v_lshl_add_u64 v[64:65], v[64:65], 2, s[14:15]
	v_lshl_add_u64 v[66:67], v[66:67], 2, s[14:15]
	v_mov_b32_e32 v158, v64
	v_mov_b32_e32 v159, v65
	global_load_dword v126, v[158:159], off
	global_load_dword v128, v[158:159], off offset:16
	global_load_dword v130, v[158:159], off offset:32
	global_load_dword v132, v[158:159], off offset:48
	global_load_dword v134, v[158:159], off offset:64
	global_load_dword v136, v[158:159], off offset:80
	global_load_dword v138, v[158:159], off offset:96
	global_load_dword v140, v[158:159], off offset:112
	global_load_dword v142, v[158:159], off offset:128
	global_load_dword v144, v[158:159], off offset:144
	global_load_dword v146, v[158:159], off offset:160
	global_load_dword v148, v[158:159], off offset:176
	global_load_dword v150, v[158:159], off offset:192
	global_load_dword v152, v[158:159], off offset:208
	global_load_dword v154, v[158:159], off offset:224
	global_load_dword v156, v[158:159], off offset:240
	s_nop 0
	s_waitcnt vmcnt(15)
	v_pk_mul_f32 v[76:77], v[58:59], v[126:127] op_sel_hi:[1,0]
	v_pk_mul_f32 v[78:79], v[56:57], v[126:127] op_sel_hi:[1,0]
	s_waitcnt vmcnt(14)
	v_pk_mul_f32 v[66:67], v[62:63], v[128:129] op_sel_hi:[1,0]
	v_pk_mul_f32 v[64:65], v[60:61], v[128:129] op_sel_hi:[1,0]
	s_cbranch_execnz .LBB0_38

; #define LAS __attribute__((address_space(3)))
; __device__ __forceinline__ void tr_item(const float* __restrict__ W, int K, int N, bf16_t* __restrict__ WT, int k0, int n0, int drow0, const float* gain, LAS float* scr, int lane) {
;     ...
;     for (int i = 0; i < 16; ++i) { const int kk = 4 * i + kq_; f32x4 t = v[i];
;         if (gain) t = t * gain[k0 + kk];
;         LAS float* s = scr + kk * 65 + nn; s[0] = t[0]; s[1] = t[1]; s[2] = t[2]; s[3] = t[3]; }
.LBB0_38:
	s_load_dwordx2 s[16:17], s[4:5], 0xc8
	s_waitcnt vmcnt(15)
	v_cndmask_b32_e64 v56, 0, 1, s[18:19]
	v_cmp_ne_u32_e64 s[4:5], 1, v56
	s_andn2_b64 vcc, exec, s[18:19]
	ds_write2_b32 v91, v78, v79 offset1:1
	ds_write2_b32 v91, v76, v77 offset0:2 offset1:3
	ds_write2_b32 v123, v64, v65 offset1:1
	ds_write2_b32 v123, v66, v67 offset0:2 offset1:3
	s_cbranch_vccnz .LBB0_59
	s_ashr_i32 s11, s10, 31
	v_lshl_add_u64 v[56:57], s[10:11], 0, v[68:69]
	v_lshl_add_u64 v[56:57], v[56:57], 2, s[14:15]
	s_waitcnt vmcnt(13)
	v_pk_mul_f32 v[60:61], v[50:51], v[130:131] op_sel_hi:[1,0]
	v_pk_mul_f32 v[62:63], v[48:49], v[130:131] op_sel_hi:[1,0]
	s_waitcnt vmcnt(12)
	v_pk_mul_f32 v[58:59], v[54:55], v[132:133] op_sel_hi:[1,0]
	v_pk_mul_f32 v[56:57], v[52:53], v[132:133] op_sel_hi:[1,0]
	s_cbranch_execnz .LBB0_41

; #define LAS __attribute__((address_space(3)))
; __device__ __forceinline__ void tr_item(const float* __restrict__ W, int K, int N, bf16_t* __restrict__ WT, int k0, int n0, int drow0, const float* gain, LAS float* scr, int lane) {
;     ...
;     for (int i = 0; i < 16; ++i) { const int kk = 4 * i + kq_; f32x4 t = v[i];
;         if (gain) t = t * gain[k0 + kk];
;         LAS float* s = scr + kk * 65 + nn; s[0] = t[0]; s[1] = t[1]; s[2] = t[2]; s[3] = t[3]; }
.LBB0_41:
	s_waitcnt vmcnt(13)
	v_add_u32_e32 v48, 0x410, v123
	ds_write2_b32 v48, v62, v63 offset1:1
	v_add_u32_e32 v48, 0x418, v123
	ds_write2_b32 v48, v60, v61 offset1:1
	v_add_u32_e32 v48, 0x820, v123
	ds_write2_b32 v48, v56, v57 offset1:1
	v_add_u32_e32 v48, 0x828, v123
	s_and_b64 vcc, exec, s[4:5]
	ds_write2_b32 v48, v58, v59 offset1:1
	s_cbranch_vccnz .LBB0_60
	s_ashr_i32 s11, s10, 31
	v_lshl_add_u64 v[48:49], s[10:11], 0, v[68:69]
	v_lshl_add_u64 v[48:49], v[48:49], 2, s[14:15]
	s_waitcnt vmcnt(11)
	v_pk_mul_f32 v[52:53], v[42:43], v[134:135] op_sel_hi:[1,0]
	v_pk_mul_f32 v[54:55], v[40:41], v[134:135] op_sel_hi:[1,0]
	s_waitcnt vmcnt(10)
	v_pk_mul_f32 v[50:51], v[46:47], v[136:137] op_sel_hi:[1,0]
	v_pk_mul_f32 v[48:49], v[44:45], v[136:137] op_sel_hi:[1,0]
	s_cbranch_execnz .LBB0_44

; #define LAS __attribute__((address_space(3)))
; __device__ __forceinline__ void tr_item(const float* __restrict__ W, int K, int N, bf16_t* __restrict__ WT, int k0, int n0, int drow0, const float* gain, LAS float* scr, int lane) {
;     ...
;     for (int i = 0; i < 16; ++i) { const int kk = 4 * i + kq_; f32x4 t = v[i];
;         if (gain) t = t * gain[k0 + kk];
;         LAS float* s = scr + kk * 65 + nn; s[0] = t[0]; s[1] = t[1]; s[2] = t[2]; s[3] = t[3]; }
.LBB0_44:
	s_waitcnt vmcnt(11)
	v_add_u32_e32 v40, 0xc30, v123
	ds_write2_b32 v40, v54, v55 offset1:1
	v_add_u32_e32 v40, 0xc38, v123
	ds_write2_b32 v40, v52, v53 offset1:1
	v_add_u32_e32 v40, 0x1040, v123
	ds_write2_b32 v40, v48, v49 offset1:1
	v_add_u32_e32 v40, 0x1048, v123
	s_and_b64 vcc, exec, s[4:5]
	ds_write2_b32 v40, v50, v51 offset1:1
	s_cbranch_vccnz .LBB0_61
	s_ashr_i32 s11, s10, 31
	v_lshl_add_u64 v[40:41], s[10:11], 0, v[68:69]
	v_lshl_add_u64 v[40:41], v[40:41], 2, s[14:15]
	s_waitcnt vmcnt(9)
	v_pk_mul_f32 v[44:45], v[34:35], v[138:139] op_sel_hi:[1,0]
	v_pk_mul_f32 v[46:47], v[32:33], v[138:139] op_sel_hi:[1,0]
	s_waitcnt vmcnt(8)
	v_pk_mul_f32 v[42:43], v[38:39], v[140:141] op_sel_hi:[1,0]
	v_pk_mul_f32 v[40:41], v[36:37], v[140:141] op_sel_hi:[1,0]
	s_cbranch_execnz .LBB0_47

; #define LAS __attribute__((address_space(3)))
; __device__ __forceinline__ void tr_item(const float* __restrict__ W, int K, int N, bf16_t* __restrict__ WT, int k0, int n0, int drow0, const float* gain, LAS float* scr, int lane) {
;     ...
;     for (int i = 0; i < 16; ++i) { const int kk = 4 * i + kq_; f32x4 t = v[i];
;         if (gain) t = t * gain[k0 + kk];
;         LAS float* s = scr + kk * 65 + nn; s[0] = t[0]; s[1] = t[1]; s[2] = t[2]; s[3] = t[3]; }
.LBB0_47:
	s_waitcnt vmcnt(9)
	v_add_u32_e32 v32, 0x1450, v123
	ds_write2_b32 v32, v46, v47 offset1:1
	v_add_u32_e32 v32, 0x1458, v123
	ds_write2_b32 v32, v44, v45 offset1:1
	v_add_u32_e32 v32, 0x1860, v123
	ds_write2_b32 v32, v40, v41 offset1:1
	v_add_u32_e32 v32, 0x1868, v123
	s_and_b64 vcc, exec, s[4:5]
	ds_write2_b32 v32, v42, v43 offset1:1
	s_cbranch_vccnz .LBB0_62
	s_ashr_i32 s11, s10, 31
	v_lshl_add_u64 v[32:33], s[10:11], 0, v[68:69]
	v_lshl_add_u64 v[32:33], v[32:33], 2, s[14:15]
	s_waitcnt vmcnt(7)
	v_pk_mul_f32 v[36:37], v[26:27], v[142:143] op_sel_hi:[1,0]
	v_pk_mul_f32 v[38:39], v[24:25], v[142:143] op_sel_hi:[1,0]
	s_waitcnt vmcnt(6)
	v_pk_mul_f32 v[34:35], v[30:31], v[144:145] op_sel_hi:[1,0]
	v_pk_mul_f32 v[32:33], v[28:29], v[144:145] op_sel_hi:[1,0]
	s_cbranch_execnz .LBB0_50

; #define LAS __attribute__((address_space(3)))
; __device__ __forceinline__ void tr_item(const float* __restrict__ W, int K, int N, bf16_t* __restrict__ WT, int k0, int n0, int drow0, const float* gain, LAS float* scr, int lane) {
;     ...
;     for (int i = 0; i < 16; ++i) { const int kk = 4 * i + kq_; f32x4 t = v[i];
;         if (gain) t = t * gain[k0 + kk];
;         LAS float* s = scr + kk * 65 + nn; s[0] = t[0]; s[1] = t[1]; s[2] = t[2]; s[3] = t[3]; }
.LBB0_50:
	s_waitcnt vmcnt(7)
	v_add_u32_e32 v24, 0x1c70, v123
	ds_write2_b32 v24, v38, v39 offset1:1
	v_add_u32_e32 v24, 0x1c78, v123
	ds_write2_b32 v24, v36, v37 offset1:1
	v_add_u32_e32 v24, 0x2080, v123
	ds_write2_b32 v24, v32, v33 offset1:1
	v_add_u32_e32 v24, 0x2088, v123
	s_and_b64 vcc, exec, s[4:5]
	ds_write2_b32 v24, v34, v35 offset1:1
	s_cbranch_vccnz .LBB0_63
	s_ashr_i32 s11, s10, 31
	v_lshl_add_u64 v[24:25], s[10:11], 0, v[68:69]
	v_lshl_add_u64 v[24:25], v[24:25], 2, s[14:15]
	s_waitcnt vmcnt(5)
	v_pk_mul_f32 v[28:29], v[18:19], v[146:147] op_sel_hi:[1,0]
	v_pk_mul_f32 v[30:31], v[16:17], v[146:147] op_sel_hi:[1,0]
	s_waitcnt vmcnt(4)
	v_pk_mul_f32 v[26:27], v[22:23], v[148:149] op_sel_hi:[1,0]
	v_pk_mul_f32 v[24:25], v[20:21], v[148:149] op_sel_hi:[1,0]
	s_cbranch_execnz .LBB0_53

; #define LAS __attribute__((address_space(3)))
; __device__ __forceinline__ void tr_item(const float* __restrict__ W, int K, int N, bf16_t* __restrict__ WT, int k0, int n0, int drow0, const float* gain, LAS float* scr, int lane) {
;     ...
;     for (int i = 0; i < 16; ++i) { const int kk = 4 * i + kq_; f32x4 t = v[i];
;         if (gain) t = t * gain[k0 + kk];
;         LAS float* s = scr + kk * 65 + nn; s[0] = t[0]; s[1] = t[1]; s[2] = t[2]; s[3] = t[3]; }
.LBB0_53:
	s_waitcnt vmcnt(5)
	v_add_u32_e32 v16, 0x2490, v123
	ds_write2_b32 v16, v30, v31 offset1:1
	v_add_u32_e32 v16, 0x2498, v123
	ds_write2_b32 v16, v28, v29 offset1:1
	v_add_u32_e32 v16, 0x28a0, v123
	ds_write2_b32 v16, v24, v25 offset1:1
	v_add_u32_e32 v16, 0x28a8, v123
	s_and_b64 vcc, exec, s[4:5]
	ds_write2_b32 v16, v26, v27 offset1:1
	s_cbranch_vccnz .LBB0_64
	s_ashr_i32 s11, s10, 31
	v_lshl_add_u64 v[16:17], s[10:11], 0, v[68:69]
	v_lshl_add_u64 v[16:17], v[16:17], 2, s[14:15]
	s_waitcnt vmcnt(3)
	v_pk_mul_f32 v[20:21], v[10:11], v[150:151] op_sel_hi:[1,0]
	v_pk_mul_f32 v[22:23], v[8:9], v[150:151] op_sel_hi:[1,0]
	s_waitcnt vmcnt(2)
	v_pk_mul_f32 v[18:19], v[14:15], v[152:153] op_sel_hi:[1,0]
	v_pk_mul_f32 v[16:17], v[12:13], v[152:153] op_sel_hi:[1,0]
	s_cbranch_execnz .LBB0_56

; #define LAS __attribute__((address_space(3)))
; __device__ __forceinline__ void tr_item(const float* __restrict__ W, int K, int N, bf16_t* __restrict__ WT, int k0, int n0, int drow0, const float* gain, LAS float* scr, int lane) {
;     ...
;     for (int i = 0; i < 16; ++i) { const int kk = 4 * i + kq_; f32x4 t = v[i];
;         if (gain) t = t * gain[k0 + kk];
;         LAS float* s = scr + kk * 65 + nn; s[0] = t[0]; s[1] = t[1]; s[2] = t[2]; s[3] = t[3]; }
.LBB0_56:
	s_waitcnt vmcnt(3)
	v_add_u32_e32 v8, 0x2cb0, v123
	ds_write2_b32 v8, v22, v23 offset1:1
	v_add_u32_e32 v8, 0x2cb8, v123
	ds_write2_b32 v8, v20, v21 offset1:1
	v_add_u32_e32 v8, 0x30c0, v123
	ds_write2_b32 v8, v16, v17 offset1:1
	v_add_u32_e32 v8, 0x30c8, v123
	s_and_b64 vcc, exec, s[4:5]
	ds_write2_b32 v8, v18, v19 offset1:1
	s_cbranch_vccnz .LBB0_65
	s_ashr_i32 s11, s10, 31
	v_lshl_add_u64 v[8:9], s[10:11], 0, v[68:69]
	v_lshl_add_u64 v[8:9], v[8:9], 2, s[14:15]
	s_waitcnt vmcnt(1)
	v_pk_mul_f32 v[12:13], v[2:3], v[154:155] op_sel_hi:[1,0]
	v_pk_mul_f32 v[14:15], v[0:1], v[154:155] op_sel_hi:[1,0]
	s_waitcnt vmcnt(0)
	v_pk_mul_f32 v[10:11], v[6:7], v[156:157] op_sel_hi:[1,0]
	v_pk_mul_f32 v[8:9], v[4:5], v[156:157] op_sel_hi:[1,0]
	s_cbranch_execnz .LBB0_24
	s_branch .LBB0_66

; #define LAS __attribute__((address_space(3)))
; __device__ __forceinline__ int pair_row(int n0, int H) { const int gsel = n0 >= H ? 1 : 0, nn = n0 - gsel * H; return (nn >> 7) * 256 + gsel * 128 + (nn & 127); }
; __device__ __forceinline__ void tr_item(const float* __restrict__ W, int K, int N, bf16_t* __restrict__ WT, int k0, int n0, int drow0, const float* gain, LAS float* scr, int lane) {
;     f32x4 v[16];
;     const int kq_ = lane >> 4, nn = (lane & 15) * 4;
; #pragma unroll
;     for (int i = 0; i < 16; ++i) v[i] = __builtin_nontemporal_load((const f32x4*)(W + (size_t)(k0 + 4 * i + kq_) * N + n0 + nn));
; #pragma unroll
;     for (int i = 0; i < 16; ++i) { const int kk = 4 * i + kq_; f32x4 t = v[i];
;         if (gain) t = t * gain[k0 + kk];
;         LAS float* s = scr + kk * 65 + nn; s[0] = t[0]; s[1] = t[1]; s[2] = t[2]; s[3] = t[3]; }
; __device__ __forceinline__ bool tr_matrix(int& it, const float* W, int K, int N, bf16_t* WT, int drow_base, int pairH, const float* gain, LAS float* scr, int lane) {
;     const int nb = N / 64, cnt = (K / 64) * nb;
;     if (it >= cnt) { it -= cnt; return false; }
;     const int kb = it / nb, n0 = (it % nb) * 64;
;     tr_item(W, K, N, WT, kb * 64, n0, drow_base + (pairH ? pair_row(n0, pairH) : n0), gain, scr, lane);
;     return true;
.LBB0_1143:
	s_ashr_i32 s55, s54, 31
	s_lshl_b64 s[28:29], s[54:55], 3
	s_add_u32 s28, s0, s28
	s_addc_u32 s29, s1, s29
	s_ashr_i32 s7, s6, 31
	s_lshl_b64 s[6:7], s[6:7], 3
	s_add_u32 s6, s0, s6
	s_addc_u32 s7, s1, s7
	s_ashr_i32 s17, s16, 31
	s_lshl_b64 s[16:17], s[16:17], 3
	s_add_u32 s16, s0, s16
	s_addc_u32 s17, s1, s17
	s_load_dwordx2 s[30:31], s[16:17], 0x8
	s_mul_hi_i32 s3, s27, 0x2aaaaaab
	s_load_dwordx2 s[28:29], s[28:29], 0x30
	v_lshlrev_b32_e32 v96, 2, v70
	s_waitcnt lgkmcnt(0)
	s_add_u32 s58, s30, s14
	s_addc_u32 s59, s31, s15
	s_lshr_b32 s16, s3, 31
	s_ashr_i32 s3, s3, 4
	s_add_i32 s3, s3, s16
	s_mul_i32 s16, s3, 0x60
	s_sub_i32 s16, s27, s16
	s_lshl_b32 s54, s16, 6
	s_ashr_i32 s55, s54, 31
	s_lshl_b32 s16, s3, 6
	s_lshl_b64 s[42:43], s[54:55], 2
	s_add_u32 s28, s28, s42
	v_or_b32_e32 v64, s16, v68
	s_addc_u32 s29, s29, s43
	v_lshl_add_u64 v[0:1], s[28:29], 0, v[96:97]
	v_or_b32_e32 v4, 4, v64
	v_mad_i64_i32 v[2:3], s[28:29], v64, s33, v[0:1]
	v_mad_i64_i32 v[4:5], s[28:29], v4, s33, v[0:1]
	global_load_dwordx4 v[56:59], v[2:3], off nt
	global_load_dwordx4 v[60:63], v[4:5], off nt
	v_or_b32_e32 v2, 8, v64
	v_or_b32_e32 v4, 12, v64
	v_mad_i64_i32 v[2:3], s[28:29], v2, s33, v[0:1]
	v_mad_i64_i32 v[4:5], s[28:29], v4, s33, v[0:1]
	global_load_dwordx4 v[48:51], v[2:3], off nt
	global_load_dwordx4 v[52:55], v[4:5], off nt
	v_or_b32_e32 v2, 16, v64
	v_or_b32_e32 v4, 20, v64
	v_mad_i64_i32 v[2:3], s[28:29], v2, s33, v[0:1]
	v_mad_i64_i32 v[4:5], s[28:29], v4, s33, v[0:1]
	global_load_dwordx4 v[40:43], v[2:3], off nt
	global_load_dwordx4 v[44:47], v[4:5], off nt
	v_or_b32_e32 v2, 24, v64
	v_or_b32_e32 v4, 28, v64
	v_mad_i64_i32 v[2:3], s[28:29], v2, s33, v[0:1]
	v_mad_i64_i32 v[4:5], s[28:29], v4, s33, v[0:1]
	global_load_dwordx4 v[32:35], v[2:3], off nt
	global_load_dwordx4 v[36:39], v[4:5], off nt
	v_or_b32_e32 v2, 32, v64
	v_or_b32_e32 v4, 36, v64
	v_mad_i64_i32 v[2:3], s[28:29], v2, s33, v[0:1]
	v_mad_i64_i32 v[4:5], s[28:29], v4, s33, v[0:1]
	global_load_dwordx4 v[24:27], v[2:3], off nt
	global_load_dwordx4 v[28:31], v[4:5], off nt
	v_or_b32_e32 v2, 40, v64
	v_or_b32_e32 v4, 44, v64
	v_mad_i64_i32 v[2:3], s[28:29], v2, s33, v[0:1]
	v_mad_i64_i32 v[4:5], s[28:29], v4, s33, v[0:1]
	global_load_dwordx4 v[16:19], v[2:3], off nt
	global_load_dwordx4 v[20:23], v[4:5], off nt
	v_or_b32_e32 v2, 48, v64
	v_or_b32_e32 v4, 52, v64
	v_mad_i64_i32 v[2:3], s[28:29], v2, s33, v[0:1]
	v_mad_i64_i32 v[4:5], s[28:29], v4, s33, v[0:1]
	global_load_dwordx4 v[8:11], v[2:3], off nt
	global_load_dwordx4 v[12:15], v[4:5], off nt
	v_or_b32_e32 v2, 56, v64
	v_or_b32_e32 v4, 60, v64
	v_mad_i64_i32 v[2:3], s[28:29], v2, s33, v[0:1]
	v_mad_i64_i32 v[4:5], s[28:29], v4, s33, v[0:1]
	global_load_dwordx4 v[0:3], v[2:3], off nt
	s_nop 0
	global_load_dwordx4 v[4:7], v[4:5], off nt
	s_cmp_lg_u64 s[30:31], 0
	s_cselect_b64 s[56:57], -1, 0
	s_cmp_eq_u64 s[30:31], 0
	s_cbranch_scc1 .LBB0_1204
	s_ashr_i32 s17, s16, 31
	v_ashrrev_i32_e32 v65, 31, v64
	v_lshl_add_u64 v[66:67], s[16:17], 0, v[68:69]
	v_lshl_add_u64 v[64:65], v[64:65], 2, s[58:59]
	v_lshl_add_u64 v[66:67], v[66:67], 2, s[58:59]
	v_mov_b32_e32 v158, v64
	v_mov_b32_e32 v159, v65
	global_load_dword v126, v[158:159], off
	global_load_dword v128, v[158:159], off offset:16
	global_load_dword v130, v[158:159], off offset:32
	global_load_dword v132, v[158:159], off offset:48
	global_load_dword v134, v[158:159], off offset:64
	global_load_dword v136, v[158:159], off offset:80
	global_load_dword v138, v[158:159], off offset:96
	global_load_dword v140, v[158:159], off offset:112
	global_load_dword v142, v[158:159], off offset:128
	global_load_dword v144, v[158:159], off offset:144
	global_load_dword v146, v[158:159], off offset:160
	global_load_dword v148, v[158:159], off offset:176
	global_load_dword v150, v[158:159], off offset:192
	global_load_dword v152, v[158:159], off offset:208
	global_load_dword v154, v[158:159], off offset:224
	global_load_dword v156, v[158:159], off offset:240
	s_nop 0
	s_waitcnt vmcnt(15)
	v_pk_mul_f32 v[74:75], v[58:59], v[126:127] op_sel_hi:[1,0]
	v_pk_mul_f32 v[76:77], v[56:57], v[126:127] op_sel_hi:[1,0]
	s_waitcnt vmcnt(14)
	v_pk_mul_f32 v[66:67], v[62:63], v[128:129] op_sel_hi:[1,0]
	v_pk_mul_f32 v[64:65], v[60:61], v[128:129] op_sel_hi:[1,0]
	s_cbranch_execnz .LBB0_1146

; #define LAS __attribute__((address_space(3)))
; __device__ __forceinline__ void tr_item(const float* __restrict__ W, int K, int N, bf16_t* __restrict__ WT, int k0, int n0, int drow0, const float* gain, LAS float* scr, int lane) {
;     ...
;     for (int i = 0; i < 16; ++i) { const int kk = 4 * i + kq_; f32x4 t = v[i];
;         if (gain) t = t * gain[k0 + kk];
;         LAS float* s = scr + kk * 65 + nn; s[0] = t[0]; s[1] = t[1]; s[2] = t[2]; s[3] = t[3]; }
.LBB0_1146:
	s_load_dwordx2 s[60:61], s[6:7], 0xc8
	s_waitcnt vmcnt(15)
	v_cndmask_b32_e64 v57, 0, 1, s[56:57]
	v_add_u32_e32 v56, v71, v87
	v_cmp_ne_u32_e64 s[6:7], 1, v57
	s_andn2_b64 vcc, exec, s[56:57]
	ds_write2_b32 v73, v76, v77 offset1:1
	ds_write2_b32 v73, v74, v75 offset0:2 offset1:3
	ds_write2_b32 v56, v64, v65 offset1:1
	ds_write2_b32 v56, v66, v67 offset0:2 offset1:3
	s_cbranch_vccnz .LBB0_1205
	s_ashr_i32 s17, s16, 31
	v_lshl_add_u64 v[56:57], s[16:17], 0, v[68:69]
	v_lshl_add_u64 v[56:57], v[56:57], 2, s[58:59]
	s_nop 0
	s_waitcnt vmcnt(13)
	v_pk_mul_f32 v[60:61], v[50:51], v[130:131] op_sel_hi:[1,0]
	v_pk_mul_f32 v[62:63], v[48:49], v[130:131] op_sel_hi:[1,0]
	s_waitcnt vmcnt(12)
	v_pk_mul_f32 v[58:59], v[54:55], v[132:133] op_sel_hi:[1,0]
	v_pk_mul_f32 v[56:57], v[52:53], v[132:133] op_sel_hi:[1,0]
	s_cbranch_execnz .LBB0_1149

; #define LAS __attribute__((address_space(3)))
; __device__ __forceinline__ void tr_item(const float* __restrict__ W, int K, int N, bf16_t* __restrict__ WT, int k0, int n0, int drow0, const float* gain, LAS float* scr, int lane) {
;     ...
;     for (int i = 0; i < 16; ++i) { const int kk = 4 * i + kq_; f32x4 t = v[i];
;         if (gain) t = t * gain[k0 + kk];
;         LAS float* s = scr + kk * 65 + nn; s[0] = t[0]; s[1] = t[1]; s[2] = t[2]; s[3] = t[3]; }
.LBB0_1149:
	s_waitcnt vmcnt(13)
	v_add_u32_e32 v48, v71, v88
	ds_write2_b32 v48, v62, v63 offset1:1
	ds_write2_b32 v48, v60, v61 offset0:2 offset1:3
	v_add_u32_e32 v49, 0x410, v48
	v_add_u32_e32 v48, 0x418, v48
	s_and_b64 vcc, exec, s[6:7]
	ds_write2_b32 v49, v56, v57 offset1:1
	ds_write2_b32 v48, v58, v59 offset1:1
	s_cbranch_vccnz .LBB0_1206
	s_ashr_i32 s17, s16, 31
	v_lshl_add_u64 v[48:49], s[16:17], 0, v[68:69]
	v_lshl_add_u64 v[48:49], v[48:49], 2, s[58:59]
	s_nop 0
	s_waitcnt vmcnt(11)
	v_pk_mul_f32 v[52:53], v[42:43], v[134:135] op_sel_hi:[1,0]
	v_pk_mul_f32 v[54:55], v[40:41], v[134:135] op_sel_hi:[1,0]
	s_waitcnt vmcnt(10)
	v_pk_mul_f32 v[50:51], v[46:47], v[136:137] op_sel_hi:[1,0]
	v_pk_mul_f32 v[48:49], v[44:45], v[136:137] op_sel_hi:[1,0]
	s_cbranch_execnz .LBB0_1152

; #define LAS __attribute__((address_space(3)))
; __device__ __forceinline__ void tr_item(const float* __restrict__ W, int K, int N, bf16_t* __restrict__ WT, int k0, int n0, int drow0, const float* gain, LAS float* scr, int lane) {
;     ...
;     for (int i = 0; i < 16; ++i) { const int kk = 4 * i + kq_; f32x4 t = v[i];
;         if (gain) t = t * gain[k0 + kk];
;         LAS float* s = scr + kk * 65 + nn; s[0] = t[0]; s[1] = t[1]; s[2] = t[2]; s[3] = t[3]; }
.LBB0_1152:
	s_waitcnt vmcnt(11)
	v_add_u32_e32 v40, v71, v89
	ds_write2_b32 v40, v54, v55 offset1:1
	ds_write2_b32 v40, v52, v53 offset0:2 offset1:3
	v_add_u32_e32 v41, 0x410, v40
	v_add_u32_e32 v40, 0x418, v40
	s_and_b64 vcc, exec, s[6:7]
	ds_write2_b32 v41, v48, v49 offset1:1
	ds_write2_b32 v40, v50, v51 offset1:1
	s_cbranch_vccnz .LBB0_1207
	s_ashr_i32 s17, s16, 31
	v_lshl_add_u64 v[40:41], s[16:17], 0, v[68:69]
	v_lshl_add_u64 v[40:41], v[40:41], 2, s[58:59]
	s_nop 0
	s_waitcnt vmcnt(9)
	v_pk_mul_f32 v[44:45], v[34:35], v[138:139] op_sel_hi:[1,0]
	v_pk_mul_f32 v[46:47], v[32:33], v[138:139] op_sel_hi:[1,0]
	s_waitcnt vmcnt(8)
	v_pk_mul_f32 v[42:43], v[38:39], v[140:141] op_sel_hi:[1,0]
	v_pk_mul_f32 v[40:41], v[36:37], v[140:141] op_sel_hi:[1,0]
	s_cbranch_execnz .LBB0_1155

; #define LAS __attribute__((address_space(3)))
; __device__ __forceinline__ void tr_item(const float* __restrict__ W, int K, int N, bf16_t* __restrict__ WT, int k0, int n0, int drow0, const float* gain, LAS float* scr, int lane) {
;     ...
;     for (int i = 0; i < 16; ++i) { const int kk = 4 * i + kq_; f32x4 t = v[i];
;         if (gain) t = t * gain[k0 + kk];
;         LAS float* s = scr + kk * 65 + nn; s[0] = t[0]; s[1] = t[1]; s[2] = t[2]; s[3] = t[3]; }
.LBB0_1155:
	v_add_u32_e32 v48, v71, v90
	s_waitcnt vmcnt(9)
	v_add_u32_e32 v32, 0x410, v48
	ds_write2_b32 v48, v46, v47 offset1:1
	ds_write2_b32 v48, v44, v45 offset0:2 offset1:3
	ds_write2_b32 v32, v40, v41 offset1:1
	v_add_u32_e32 v32, 0x418, v48
	s_and_b64 vcc, exec, s[6:7]
	ds_write2_b32 v32, v42, v43 offset1:1
	s_cbranch_vccnz .LBB0_1208
	s_ashr_i32 s17, s16, 31
	v_lshl_add_u64 v[32:33], s[16:17], 0, v[68:69]
	v_lshl_add_u64 v[32:33], v[32:33], 2, s[58:59]
	s_nop 0
	s_waitcnt vmcnt(7)
	v_pk_mul_f32 v[36:37], v[26:27], v[142:143] op_sel_hi:[1,0]
	v_pk_mul_f32 v[38:39], v[24:25], v[142:143] op_sel_hi:[1,0]
	s_waitcnt vmcnt(6)
	v_pk_mul_f32 v[34:35], v[30:31], v[144:145] op_sel_hi:[1,0]
	v_pk_mul_f32 v[32:33], v[28:29], v[144:145] op_sel_hi:[1,0]
	s_cbranch_execnz .LBB0_1158

; #define LAS __attribute__((address_space(3)))
; __device__ __forceinline__ void tr_item(const float* __restrict__ W, int K, int N, bf16_t* __restrict__ WT, int k0, int n0, int drow0, const float* gain, LAS float* scr, int lane) {
;     ...
;     for (int i = 0; i < 16; ++i) { const int kk = 4 * i + kq_; f32x4 t = v[i];
;         if (gain) t = t * gain[k0 + kk];
;         LAS float* s = scr + kk * 65 + nn; s[0] = t[0]; s[1] = t[1]; s[2] = t[2]; s[3] = t[3]; }
.LBB0_1158:
	s_waitcnt vmcnt(7)
	v_add_u32_e32 v24, 0x820, v48
	ds_write2_b32 v24, v38, v39 offset1:1
	v_add_u32_e32 v24, 0x828, v48
	ds_write2_b32 v24, v36, v37 offset1:1
	v_add_u32_e32 v24, 0xc30, v48
	ds_write2_b32 v24, v32, v33 offset1:1
	v_add_u32_e32 v24, 0xc38, v48
	s_and_b64 vcc, exec, s[6:7]
	ds_write2_b32 v24, v34, v35 offset1:1
	s_cbranch_vccnz .LBB0_1209
	s_ashr_i32 s17, s16, 31
	v_lshl_add_u64 v[24:25], s[16:17], 0, v[68:69]
	v_lshl_add_u64 v[24:25], v[24:25], 2, s[58:59]
	s_nop 0
	s_waitcnt vmcnt(5)
	v_pk_mul_f32 v[28:29], v[18:19], v[146:147] op_sel_hi:[1,0]
	v_pk_mul_f32 v[30:31], v[16:17], v[146:147] op_sel_hi:[1,0]
	s_waitcnt vmcnt(4)
	v_pk_mul_f32 v[26:27], v[22:23], v[148:149] op_sel_hi:[1,0]
	v_pk_mul_f32 v[24:25], v[20:21], v[148:149] op_sel_hi:[1,0]
	s_cbranch_execnz .LBB0_1161

; #define LAS __attribute__((address_space(3)))
; __device__ __forceinline__ void tr_item(const float* __restrict__ W, int K, int N, bf16_t* __restrict__ WT, int k0, int n0, int drow0, const float* gain, LAS float* scr, int lane) {
;     ...
;     for (int i = 0; i < 16; ++i) { const int kk = 4 * i + kq_; f32x4 t = v[i];
;         if (gain) t = t * gain[k0 + kk];
;         LAS float* s = scr + kk * 65 + nn; s[0] = t[0]; s[1] = t[1]; s[2] = t[2]; s[3] = t[3]; }
.LBB0_1161:
	s_waitcnt vmcnt(5)
	v_add_u32_e32 v16, 0x1040, v48
	ds_write2_b32 v16, v30, v31 offset1:1
	v_add_u32_e32 v16, 0x1048, v48
	ds_write2_b32 v16, v28, v29 offset1:1
	v_add_u32_e32 v16, 0x1450, v48
	ds_write2_b32 v16, v24, v25 offset1:1
	v_add_u32_e32 v16, 0x1458, v48
	s_and_b64 vcc, exec, s[6:7]
	ds_write2_b32 v16, v26, v27 offset1:1
	s_cbranch_vccnz .LBB0_1210
	s_ashr_i32 s17, s16, 31
	v_lshl_add_u64 v[16:17], s[16:17], 0, v[68:69]
	v_lshl_add_u64 v[16:17], v[16:17], 2, s[58:59]
	s_nop 0
	s_waitcnt vmcnt(3)
	v_pk_mul_f32 v[20:21], v[10:11], v[150:151] op_sel_hi:[1,0]
	v_pk_mul_f32 v[22:23], v[8:9], v[150:151] op_sel_hi:[1,0]
	s_waitcnt vmcnt(2)
	v_pk_mul_f32 v[18:19], v[14:15], v[152:153] op_sel_hi:[1,0]
	v_pk_mul_f32 v[16:17], v[12:13], v[152:153] op_sel_hi:[1,0]
	s_cbranch_execnz .LBB0_1164

; #define LAS __attribute__((address_space(3)))
; __device__ __forceinline__ void tr_item(const float* __restrict__ W, int K, int N, bf16_t* __restrict__ WT, int k0, int n0, int drow0, const float* gain, LAS float* scr, int lane) {
;     ...
;     for (int i = 0; i < 16; ++i) { const int kk = 4 * i + kq_; f32x4 t = v[i];
;         if (gain) t = t * gain[k0 + kk];
;         LAS float* s = scr + kk * 65 + nn; s[0] = t[0]; s[1] = t[1]; s[2] = t[2]; s[3] = t[3]; }
.LBB0_1164:
	s_waitcnt vmcnt(3)
	v_add_u32_e32 v8, 0x1860, v48
	ds_write2_b32 v8, v22, v23 offset1:1
	v_add_u32_e32 v8, 0x1868, v48
	ds_write2_b32 v8, v20, v21 offset1:1
	v_add_u32_e32 v8, 0x1c70, v48
	ds_write2_b32 v8, v16, v17 offset1:1
	v_add_u32_e32 v8, 0x1c78, v48
	s_and_b64 vcc, exec, s[6:7]
	ds_write2_b32 v8, v18, v19 offset1:1
	s_cbranch_vccnz .LBB0_1211
	s_ashr_i32 s17, s16, 31
	v_lshl_add_u64 v[8:9], s[16:17], 0, v[68:69]
	v_lshl_add_u64 v[8:9], v[8:9], 2, s[58:59]
	s_nop 0
	s_waitcnt vmcnt(1)
	v_pk_mul_f32 v[12:13], v[2:3], v[154:155] op_sel_hi:[1,0]
	v_pk_mul_f32 v[14:15], v[0:1], v[154:155] op_sel_hi:[1,0]
	s_waitcnt vmcnt(0)
	v_pk_mul_f32 v[10:11], v[6:7], v[156:157] op_sel_hi:[1,0]
	v_pk_mul_f32 v[8:9], v[4:5], v[156:157] op_sel_hi:[1,0]
	s_cbranch_execnz .LBB0_1167

; #define LAS __attribute__((address_space(3)))
; __device__ __forceinline__ int pair_row(int n0, int H) { const int gsel = n0 >= H ? 1 : 0, nn = n0 - gsel * H; return (nn >> 7) * 256 + gsel * 128 + (nn & 127); }
; __device__ __forceinline__ void tr_item(const float* __restrict__ W, int K, int N, bf16_t* __restrict__ WT, int k0, int n0, int drow0, const float* gain, LAS float* scr, int lane) {
;     f32x4 v[16];
;     const int kq_ = lane >> 4, nn = (lane & 15) * 4;
; #pragma unroll
;     for (int i = 0; i < 16; ++i) v[i] = __builtin_nontemporal_load((const f32x4*)(W + (size_t)(k0 + 4 * i + kq_) * N + n0 + nn));
; #pragma unroll
;     for (int i = 0; i < 16; ++i) { const int kk = 4 * i + kq_; f32x4 t = v[i];
;         if (gain) t = t * gain[k0 + kk];
;         LAS float* s = scr + kk * 65 + nn; s[0] = t[0]; s[1] = t[1]; s[2] = t[2]; s[3] = t[3]; }
; __device__ __forceinline__ bool tr_matrix(int& it, const float* W, int K, int N, bf16_t* WT, int drow_base, int pairH, const float* gain, LAS float* scr, int lane) {
;     const int nb = N / 64, cnt = (K / 64) * nb;
;     if (it >= cnt) { it -= cnt; return false; }
;     const int kb = it / nb, n0 = (it % nb) * 64;
;     tr_item(W, K, N, WT, kb * 64, n0, drow_base + (pairH ? pair_row(n0, pairH) : n0), gain, scr, lane);
;     return true;
.LBB0_1179:
	s_and_b64 vcc, exec, s[6:7]
	s_cbranch_vccz .LBB0_1131
	s_mov_b32 s52, 0
	s_mov_b32 s6, 0
	s_mov_b32 s16, 0
	s_cmpk_gt_i32 s27, 0x15ff
	s_cbranch_scc1 .LBB0_1131
	s_ashr_i32 s53, s52, 31
	s_lshl_b64 s[28:29], s[52:53], 3
	s_add_u32 s28, s0, s28
	s_addc_u32 s29, s1, s29
	s_ashr_i32 s7, s6, 31
	s_lshl_b64 s[6:7], s[6:7], 3
	s_add_u32 s6, s0, s6
	s_addc_u32 s7, s1, s7
	s_ashr_i32 s17, s16, 31
	s_lshl_b64 s[16:17], s[16:17], 3
	s_add_u32 s16, s0, s16
	s_addc_u32 s17, s1, s17
	s_load_dwordx2 s[30:31], s[16:17], 0x10
	s_nop 0
	s_load_dwordx2 s[16:17], s[28:29], 0xa0
	s_mul_hi_i32 s3, s27, 0x2e8ba2e9
	v_lshlrev_b32_e32 v96, 2, v70
	s_waitcnt lgkmcnt(0)
	s_add_u32 s54, s30, s14
	s_addc_u32 s55, s31, s15
	s_add_u32 s37, s16, s18
	s_addc_u32 s17, s17, s25
	s_lshr_b32 s16, s3, 31
	s_ashr_i32 s3, s3, 5
	s_add_i32 s16, s3, s16
	s_mul_i32 s3, s16, 0xb0
	s_sub_i32 s3, s27, s3
	s_lshl_b32 s52, s3, 6
	s_ashr_i32 s53, s52, 31
	s_lshl_b32 s16, s16, 6
	s_lshl_b64 s[28:29], s[52:53], 2
	s_add_u32 s28, s37, s28
	v_or_b32_e32 v64, s16, v68
	s_addc_u32 s29, s17, s29
	v_lshl_add_u64 v[0:1], s[28:29], 0, v[96:97]
	v_or_b32_e32 v4, 4, v64
	v_mad_i64_i32 v[2:3], s[28:29], v64, s49, v[0:1]
	v_mad_i64_i32 v[4:5], s[28:29], v4, s49, v[0:1]
	global_load_dwordx4 v[56:59], v[2:3], off nt
	global_load_dwordx4 v[60:63], v[4:5], off nt
	v_or_b32_e32 v2, 8, v64
	v_or_b32_e32 v4, 12, v64
	v_mad_i64_i32 v[2:3], s[28:29], v2, s49, v[0:1]
	v_mad_i64_i32 v[4:5], s[28:29], v4, s49, v[0:1]
	global_load_dwordx4 v[48:51], v[2:3], off nt
	global_load_dwordx4 v[52:55], v[4:5], off nt
	v_or_b32_e32 v2, 16, v64
	v_or_b32_e32 v4, 20, v64
	v_mad_i64_i32 v[2:3], s[28:29], v2, s49, v[0:1]
	v_mad_i64_i32 v[4:5], s[28:29], v4, s49, v[0:1]
	global_load_dwordx4 v[40:43], v[2:3], off nt
	global_load_dwordx4 v[44:47], v[4:5], off nt
	v_or_b32_e32 v2, 24, v64
	v_or_b32_e32 v4, 28, v64
	v_mad_i64_i32 v[2:3], s[28:29], v2, s49, v[0:1]
	v_mad_i64_i32 v[4:5], s[28:29], v4, s49, v[0:1]
	global_load_dwordx4 v[32:35], v[2:3], off nt
	global_load_dwordx4 v[36:39], v[4:5], off nt
	v_or_b32_e32 v2, 32, v64
	v_or_b32_e32 v4, 36, v64
	v_mad_i64_i32 v[2:3], s[28:29], v2, s49, v[0:1]
	v_mad_i64_i32 v[4:5], s[28:29], v4, s49, v[0:1]
	global_load_dwordx4 v[24:27], v[2:3], off nt
	global_load_dwordx4 v[28:31], v[4:5], off nt
	v_or_b32_e32 v2, 40, v64
	v_or_b32_e32 v4, 44, v64
	v_mad_i64_i32 v[2:3], s[28:29], v2, s49, v[0:1]
	v_mad_i64_i32 v[4:5], s[28:29], v4, s49, v[0:1]
	global_load_dwordx4 v[16:19], v[2:3], off nt
	global_load_dwordx4 v[20:23], v[4:5], off nt
	v_or_b32_e32 v2, 48, v64
	v_or_b32_e32 v4, 52, v64
	v_mad_i64_i32 v[2:3], s[28:29], v2, s49, v[0:1]
	v_mad_i64_i32 v[4:5], s[28:29], v4, s49, v[0:1]
	global_load_dwordx4 v[8:11], v[2:3], off nt
	global_load_dwordx4 v[12:15], v[4:5], off nt
	v_or_b32_e32 v2, 56, v64
	v_or_b32_e32 v4, 60, v64
	v_mad_i64_i32 v[2:3], s[28:29], v2, s49, v[0:1]
	v_mad_i64_i32 v[4:5], s[28:29], v4, s49, v[0:1]
	global_load_dwordx4 v[0:3], v[2:3], off nt
	s_nop 0
	global_load_dwordx4 v[4:7], v[4:5], off nt
	s_cmp_lg_u64 s[30:31], 0
	s_cselect_b64 s[56:57], -1, 0
	s_cmp_eq_u64 s[30:31], 0
	s_cbranch_scc1 .LBB0_1212
	s_ashr_i32 s17, s16, 31
	v_ashrrev_i32_e32 v65, 31, v64
	v_lshl_add_u64 v[66:67], s[16:17], 0, v[68:69]
	v_lshl_add_u64 v[64:65], v[64:65], 2, s[54:55]
	v_lshl_add_u64 v[66:67], v[66:67], 2, s[54:55]
	v_mov_b32_e32 v158, v64
	v_mov_b32_e32 v159, v65
	global_load_dword v126, v[158:159], off
	global_load_dword v128, v[158:159], off offset:16
	global_load_dword v130, v[158:159], off offset:32
	global_load_dword v132, v[158:159], off offset:48
	global_load_dword v134, v[158:159], off offset:64
	global_load_dword v136, v[158:159], off offset:80
	global_load_dword v138, v[158:159], off offset:96
	global_load_dword v140, v[158:159], off offset:112
	global_load_dword v142, v[158:159], off offset:128
	global_load_dword v144, v[158:159], off offset:144
	global_load_dword v146, v[158:159], off offset:160
	global_load_dword v148, v[158:159], off offset:176
	global_load_dword v150, v[158:159], off offset:192
	global_load_dword v152, v[158:159], off offset:208
	global_load_dword v154, v[158:159], off offset:224
	global_load_dword v156, v[158:159], off offset:240
	s_nop 0
	s_waitcnt vmcnt(15)
	v_pk_mul_f32 v[74:75], v[58:59], v[126:127] op_sel_hi:[1,0]
	v_pk_mul_f32 v[76:77], v[56:57], v[126:127] op_sel_hi:[1,0]
	s_waitcnt vmcnt(14)
	v_pk_mul_f32 v[66:67], v[62:63], v[128:129] op_sel_hi:[1,0]
	v_pk_mul_f32 v[64:65], v[60:61], v[128:129] op_sel_hi:[1,0]
	s_cbranch_execnz .LBB0_1184

; #define LAS __attribute__((address_space(3)))
; __device__ __forceinline__ void tr_item(const float* __restrict__ W, int K, int N, bf16_t* __restrict__ WT, int k0, int n0, int drow0, const float* gain, LAS float* scr, int lane) {
;     ...
;     for (int i = 0; i < 16; ++i) { const int kk = 4 * i + kq_; f32x4 t = v[i];
;         if (gain) t = t * gain[k0 + kk];
;         LAS float* s = scr + kk * 65 + nn; s[0] = t[0]; s[1] = t[1]; s[2] = t[2]; s[3] = t[3]; }
.LBB0_1184:
	s_load_dwordx2 s[58:59], s[6:7], 0xc8
	s_waitcnt vmcnt(15)
	v_cndmask_b32_e64 v57, 0, 1, s[56:57]
	v_add_u32_e32 v56, v71, v87
	v_cmp_ne_u32_e64 s[6:7], 1, v57
	s_andn2_b64 vcc, exec, s[56:57]
	ds_write2_b32 v73, v76, v77 offset1:1
	ds_write2_b32 v73, v74, v75 offset0:2 offset1:3
	ds_write2_b32 v56, v64, v65 offset1:1
	ds_write2_b32 v56, v66, v67 offset0:2 offset1:3
	s_cbranch_vccnz .LBB0_1213
	s_ashr_i32 s17, s16, 31
	v_lshl_add_u64 v[56:57], s[16:17], 0, v[68:69]
	v_lshl_add_u64 v[56:57], v[56:57], 2, s[54:55]
	s_nop 0
	s_waitcnt vmcnt(13)
	v_pk_mul_f32 v[60:61], v[50:51], v[130:131] op_sel_hi:[1,0]
	v_pk_mul_f32 v[62:63], v[48:49], v[130:131] op_sel_hi:[1,0]
	s_waitcnt vmcnt(12)
	v_pk_mul_f32 v[58:59], v[54:55], v[132:133] op_sel_hi:[1,0]
	v_pk_mul_f32 v[56:57], v[52:53], v[132:133] op_sel_hi:[1,0]
	s_cbranch_execnz .LBB0_1187

; #define LAS __attribute__((address_space(3)))
; __device__ __forceinline__ void tr_item(const float* __restrict__ W, int K, int N, bf16_t* __restrict__ WT, int k0, int n0, int drow0, const float* gain, LAS float* scr, int lane) {
;     ...
;     for (int i = 0; i < 16; ++i) { const int kk = 4 * i + kq_; f32x4 t = v[i];
;         if (gain) t = t * gain[k0 + kk];
;         LAS float* s = scr + kk * 65 + nn; s[0] = t[0]; s[1] = t[1]; s[2] = t[2]; s[3] = t[3]; }
.LBB0_1187:
	s_waitcnt vmcnt(13)
	v_add_u32_e32 v48, v71, v88
	ds_write2_b32 v48, v62, v63 offset1:1
	ds_write2_b32 v48, v60, v61 offset0:2 offset1:3
	v_add_u32_e32 v49, 0x410, v48
	v_add_u32_e32 v48, 0x418, v48
	s_and_b64 vcc, exec, s[6:7]
	ds_write2_b32 v49, v56, v57 offset1:1
	ds_write2_b32 v48, v58, v59 offset1:1
	s_cbranch_vccnz .LBB0_1214
	s_ashr_i32 s17, s16, 31
	v_lshl_add_u64 v[48:49], s[16:17], 0, v[68:69]
	v_lshl_add_u64 v[48:49], v[48:49], 2, s[54:55]
	s_nop 0
	s_waitcnt vmcnt(11)
	v_pk_mul_f32 v[52:53], v[42:43], v[134:135] op_sel_hi:[1,0]
	v_pk_mul_f32 v[54:55], v[40:41], v[134:135] op_sel_hi:[1,0]
	s_waitcnt vmcnt(10)
	v_pk_mul_f32 v[50:51], v[46:47], v[136:137] op_sel_hi:[1,0]
	v_pk_mul_f32 v[48:49], v[44:45], v[136:137] op_sel_hi:[1,0]
	s_cbranch_execnz .LBB0_1190

; #define LAS __attribute__((address_space(3)))
; __device__ __forceinline__ void tr_item(const float* __restrict__ W, int K, int N, bf16_t* __restrict__ WT, int k0, int n0, int drow0, const float* gain, LAS float* scr, int lane) {
;     ...
;     for (int i = 0; i < 16; ++i) { const int kk = 4 * i + kq_; f32x4 t = v[i];
;         if (gain) t = t * gain[k0 + kk];
;         LAS float* s = scr + kk * 65 + nn; s[0] = t[0]; s[1] = t[1]; s[2] = t[2]; s[3] = t[3]; }
.LBB0_1190:
	s_waitcnt vmcnt(11)
	v_add_u32_e32 v40, v71, v89
	ds_write2_b32 v40, v54, v55 offset1:1
	ds_write2_b32 v40, v52, v53 offset0:2 offset1:3
	v_add_u32_e32 v41, 0x410, v40
	v_add_u32_e32 v40, 0x418, v40
	s_and_b64 vcc, exec, s[6:7]
	ds_write2_b32 v41, v48, v49 offset1:1
	ds_write2_b32 v40, v50, v51 offset1:1
	s_cbranch_vccnz .LBB0_1215
	s_ashr_i32 s17, s16, 31
	v_lshl_add_u64 v[40:41], s[16:17], 0, v[68:69]
	v_lshl_add_u64 v[40:41], v[40:41], 2, s[54:55]
	s_nop 0
	s_waitcnt vmcnt(9)
	v_pk_mul_f32 v[44:45], v[34:35], v[138:139] op_sel_hi:[1,0]
	v_pk_mul_f32 v[46:47], v[32:33], v[138:139] op_sel_hi:[1,0]
	s_waitcnt vmcnt(8)
	v_pk_mul_f32 v[42:43], v[38:39], v[140:141] op_sel_hi:[1,0]
	v_pk_mul_f32 v[40:41], v[36:37], v[140:141] op_sel_hi:[1,0]
	s_cbranch_execnz .LBB0_1193

; #define LAS __attribute__((address_space(3)))
; __device__ __forceinline__ void tr_item(const float* __restrict__ W, int K, int N, bf16_t* __restrict__ WT, int k0, int n0, int drow0, const float* gain, LAS float* scr, int lane) {
;     ...
;     for (int i = 0; i < 16; ++i) { const int kk = 4 * i + kq_; f32x4 t = v[i];
;         if (gain) t = t * gain[k0 + kk];
;         LAS float* s = scr + kk * 65 + nn; s[0] = t[0]; s[1] = t[1]; s[2] = t[2]; s[3] = t[3]; }
.LBB0_1193:
	v_add_u32_e32 v48, v71, v90
	s_waitcnt vmcnt(9)
	v_add_u32_e32 v32, 0x410, v48
	ds_write2_b32 v48, v46, v47 offset1:1
	ds_write2_b32 v48, v44, v45 offset0:2 offset1:3
	ds_write2_b32 v32, v40, v41 offset1:1
	v_add_u32_e32 v32, 0x418, v48
	s_and_b64 vcc, exec, s[6:7]
	ds_write2_b32 v32, v42, v43 offset1:1
	s_cbranch_vccnz .LBB0_1216
	s_ashr_i32 s17, s16, 31
	v_lshl_add_u64 v[32:33], s[16:17], 0, v[68:69]
	v_lshl_add_u64 v[32:33], v[32:33], 2, s[54:55]
	s_nop 0
	s_waitcnt vmcnt(7)
	v_pk_mul_f32 v[36:37], v[26:27], v[142:143] op_sel_hi:[1,0]
	v_pk_mul_f32 v[38:39], v[24:25], v[142:143] op_sel_hi:[1,0]
	s_waitcnt vmcnt(6)
	v_pk_mul_f32 v[34:35], v[30:31], v[144:145] op_sel_hi:[1,0]
	v_pk_mul_f32 v[32:33], v[28:29], v[144:145] op_sel_hi:[1,0]
	s_cbranch_execnz .LBB0_1196

; #define LAS __attribute__((address_space(3)))
; __device__ __forceinline__ void tr_item(const float* __restrict__ W, int K, int N, bf16_t* __restrict__ WT, int k0, int n0, int drow0, const float* gain, LAS float* scr, int lane) {
;     ...
;     for (int i = 0; i < 16; ++i) { const int kk = 4 * i + kq_; f32x4 t = v[i];
;         if (gain) t = t * gain[k0 + kk];
;         LAS float* s = scr + kk * 65 + nn; s[0] = t[0]; s[1] = t[1]; s[2] = t[2]; s[3] = t[3]; }
.LBB0_1196:
	s_waitcnt vmcnt(7)
	v_add_u32_e32 v24, 0x820, v48
	ds_write2_b32 v24, v38, v39 offset1:1
	v_add_u32_e32 v24, 0x828, v48
	ds_write2_b32 v24, v36, v37 offset1:1
	v_add_u32_e32 v24, 0xc30, v48
	ds_write2_b32 v24, v32, v33 offset1:1
	v_add_u32_e32 v24, 0xc38, v48
	s_and_b64 vcc, exec, s[6:7]
	ds_write2_b32 v24, v34, v35 offset1:1
	s_cbranch_vccnz .LBB0_1217
	s_ashr_i32 s17, s16, 31
	v_lshl_add_u64 v[24:25], s[16:17], 0, v[68:69]
	v_lshl_add_u64 v[24:25], v[24:25], 2, s[54:55]
	s_nop 0
	s_waitcnt vmcnt(5)
	v_pk_mul_f32 v[28:29], v[18:19], v[146:147] op_sel_hi:[1,0]
	v_pk_mul_f32 v[30:31], v[16:17], v[146:147] op_sel_hi:[1,0]
	s_waitcnt vmcnt(4)
	v_pk_mul_f32 v[26:27], v[22:23], v[148:149] op_sel_hi:[1,0]
	v_pk_mul_f32 v[24:25], v[20:21], v[148:149] op_sel_hi:[1,0]
	s_cbranch_execnz .LBB0_1199

; #define LAS __attribute__((address_space(3)))
; __device__ __forceinline__ void tr_item(const float* __restrict__ W, int K, int N, bf16_t* __restrict__ WT, int k0, int n0, int drow0, const float* gain, LAS float* scr, int lane) {
;     ...
;     for (int i = 0; i < 16; ++i) { const int kk = 4 * i + kq_; f32x4 t = v[i];
;         if (gain) t = t * gain[k0 + kk];
;         LAS float* s = scr + kk * 65 + nn; s[0] = t[0]; s[1] = t[1]; s[2] = t[2]; s[3] = t[3]; }
.LBB0_1199:
	s_waitcnt vmcnt(5)
	v_add_u32_e32 v16, 0x1040, v48
	ds_write2_b32 v16, v30, v31 offset1:1
	v_add_u32_e32 v16, 0x1048, v48
	ds_write2_b32 v16, v28, v29 offset1:1
	v_add_u32_e32 v16, 0x1450, v48
	ds_write2_b32 v16, v24, v25 offset1:1
	v_add_u32_e32 v16, 0x1458, v48
	s_and_b64 vcc, exec, s[6:7]
	ds_write2_b32 v16, v26, v27 offset1:1
	s_cbranch_vccnz .LBB0_1218
	s_ashr_i32 s17, s16, 31
	v_lshl_add_u64 v[16:17], s[16:17], 0, v[68:69]
	v_lshl_add_u64 v[16:17], v[16:17], 2, s[54:55]
	s_nop 0
	s_waitcnt vmcnt(3)
	v_pk_mul_f32 v[20:21], v[10:11], v[150:151] op_sel_hi:[1,0]
	v_pk_mul_f32 v[22:23], v[8:9], v[150:151] op_sel_hi:[1,0]
	s_waitcnt vmcnt(2)
	v_pk_mul_f32 v[18:19], v[14:15], v[152:153] op_sel_hi:[1,0]
	v_pk_mul_f32 v[16:17], v[12:13], v[152:153] op_sel_hi:[1,0]
	s_cbranch_execnz .LBB0_1202

; #define LAS __attribute__((address_space(3)))
; __device__ __forceinline__ void tr_item(const float* __restrict__ W, int K, int N, bf16_t* __restrict__ WT, int k0, int n0, int drow0, const float* gain, LAS float* scr, int lane) {
;     ...
;     for (int i = 0; i < 16; ++i) { const int kk = 4 * i + kq_; f32x4 t = v[i];
;         if (gain) t = t * gain[k0 + kk];
;         LAS float* s = scr + kk * 65 + nn; s[0] = t[0]; s[1] = t[1]; s[2] = t[2]; s[3] = t[3]; }
.LBB0_1202:
	s_waitcnt vmcnt(3)
	v_add_u32_e32 v8, 0x1860, v48
	ds_write2_b32 v8, v22, v23 offset1:1
	v_add_u32_e32 v8, 0x1868, v48
	ds_write2_b32 v8, v20, v21 offset1:1
	v_add_u32_e32 v8, 0x1c70, v48
	ds_write2_b32 v8, v16, v17 offset1:1
	v_add_u32_e32 v8, 0x1c78, v48
	s_and_b64 vcc, exec, s[6:7]
	ds_write2_b32 v8, v18, v19 offset1:1
	s_cbranch_vccnz .LBB0_1219
	s_ashr_i32 s17, s16, 31
	v_lshl_add_u64 v[8:9], s[16:17], 0, v[68:69]
	v_lshl_add_u64 v[8:9], v[8:9], 2, s[54:55]
	s_nop 0
	s_waitcnt vmcnt(1)
	v_pk_mul_f32 v[12:13], v[2:3], v[154:155] op_sel_hi:[1,0]
	v_pk_mul_f32 v[14:15], v[0:1], v[154:155] op_sel_hi:[1,0]
	s_waitcnt vmcnt(0)
	v_pk_mul_f32 v[10:11], v[6:7], v[156:157] op_sel_hi:[1,0]
	v_pk_mul_f32 v[8:9], v[4:5], v[156:157] op_sel_hi:[1,0]
	s_cbranch_execnz .LBB0_1130
	s_branch .LBB0_1220
